# v71 + FFN2 SwiGLU epilogue: per-row sqrt(mean+eps) of the WG's fixed row panel cached in LDS after the first tile (8 loads + vmcnt(0) + ~145 VALU skipped on tiles 2..11)
# baseline (speedup 1.0000x reference)
.LBB0_956:
	s_mov_b32 s98, -1
	v_readfirstlane_b32 s3, v220
	s_movk_i32 s0, 0x800
	s_cmpk_gt_i32 s84, 0xaff
	s_cbranch_scc1 .LBB0_977
	s_add_u32 s33, s56, 0x8200000
	s_addc_u32 s36, s57, 0
	s_add_u32 s37, s56, 0x100000
	s_addc_u32 s38, s57, 0
	s_ashr_i32 s40, s84, 31
	s_lshr_b32 s2, s40, 29
	s_add_i32 s2, s84, s2
	s_lshr_b32 s8, s3, 6
	s_ashr_i32 s1, s0, 31
	s_ashr_i32 s4, s2, 3
	s_and_b32 s2, s2, -8
	s_lshr_b32 s9, s3, 8
	s_lshl_b64 s[16:17], s[0:1], 9
	s_lshl_b64 s[18:19], s[0:1], 8
	s_lshl_b32 s39, s8, 10
	s_sub_i32 s2, s84, s2
	s_cmp_lt_i32 s2, 0
	s_movk_i32 s41, 0x161
	s_cselect_b32 s5, s41, 0x160
	s_mul_i32 s2, s2, s5
	s_add_i32 s2, s2, s4
	s_mul_hi_i32 s4, s2, 0x2e8ba2e9
	s_lshr_b32 s5, s4, 31
	s_ashr_i32 s4, s4, 6
	s_add_i32 s4, s4, s5
	s_lshl_b32 s5, s4, 3
	s_mulk_i32 s4, 0x160
	s_sub_i32 s4, s2, s4
	s_bfe_u32 s2, s4, 0x3001c
	s_add_i32 s6, s4, s2
	s_sext_i32_i16 s10, s6
	s_and_b32 s6, s6, 0xfff8
	s_sub_i32 s4, s4, s6
	s_sext_i32_i16 s4, s4
	s_add_i32 s65, s5, s4
	s_ashr_i32 s4, s65, 31
	s_mul_i32 s4, s16, s4
	s_mul_hi_u32 s5, s16, s65
	s_add_i32 s6, s5, s4
	s_lshr_b64 s[4:5], s[0:1], 23
	s_lshr_b32 s2, s10, 3
	s_mul_i32 s5, s4, s65
	s_add_i32 s12, s6, s5
	s_bfe_i64 s[6:7], s[2:3], 0x100000
	s_ashr_i32 s5, s10, 3
	s_mul_hi_u32 s6, s16, s5
	s_mul_i32 s7, s16, s7
	s_add_i32 s6, s6, s7
	s_mul_i32 s4, s4, s5
	v_mul_lo_u32 v0, s0, v152
	s_add_i32 s6, s6, s4
	s_mul_i32 s4, s16, s5
	v_add_lshl_u32 v128, v0, v148, 1
	v_mul_lo_u32 v0, s0, v151
	s_add_u32 s4, s37, s4
	v_add_lshl_u32 v130, v0, v148, 1
	v_mul_lo_u32 v0, s0, v150
	s_addc_u32 s5, s38, s6
	s_add_i32 s42, s39, 0
	v_add_lshl_u32 v132, v0, v148, 1
	s_add_i32 m0, s42, 0x10000
	s_mul_i32 s13, s16, s65
	global_load_lds_dwordx4 v132, s[4:5]
	s_add_i32 m0, s42, 0x12000
	s_add_u32 s10, s4, s18
	global_load_lds_dwordx4 v128, s[4:5]
	s_addc_u32 s11, s5, s19
	s_add_i32 m0, s42, 0x14000
	v_mul_lo_u32 v0, s0, v149
	global_load_lds_dwordx4 v132, s[10:11]
	s_add_i32 m0, s42, 0x16000
	s_add_u32 s6, s33, s13
	s_addc_u32 s7, s36, s12
	s_add_i32 s43, s42, 0x2000
	v_add_lshl_u32 v134, v0, v148, 1
	global_load_lds_dwordx4 v128, s[10:11]
	s_mov_b32 m0, s42
	s_add_u32 s12, s6, s18
	global_load_lds_dwordx4 v134, s[6:7]
	s_mov_b32 m0, s43
	s_addc_u32 s13, s7, s19
	s_add_i32 s44, s42, 0x4000
	global_load_lds_dwordx4 v130, s[6:7]
	s_mov_b32 m0, s44
	s_add_i32 s45, s42, 0x6000
	global_load_lds_dwordx4 v134, s[12:13]
	s_mov_b32 m0, s45
	v_mov_b32_e32 v137, 0
	global_load_lds_dwordx4 v130, s[12:13]
	v_mov_b32_e32 v133, v137
	v_mov_b32_e32 v129, v137
	v_mov_b32_e32 v135, v137
	v_mov_b32_e32 v131, v137
	s_cmp_eq_u32 s9, 1
	s_mov_b32 s46, 0
	v_lshl_add_u64 v[8:9], s[4:5], 0, v[132:133]
	v_lshl_add_u64 v[4:5], s[4:5], 0, v[128:129]
	v_lshl_add_u64 v[2:3], s[10:11], 0, v[132:133]
	v_lshl_add_u64 v[0:1], s[10:11], 0, v[128:129]
	v_lshl_add_u64 v[6:7], s[6:7], 0, v[134:135]
	s_cselect_b64 s[20:21], -1, 0
	s_cmp_lg_u32 s9, 1
	v_lshl_add_u64 v[10:11], s[6:7], 0, v[130:131]
	s_setprio 1
	s_cbranch_scc1 .LBB0_959
	s_setprio 0
	s_barrier

.LBB0_973:
	s_cmp_eq_u32 s65, s98
	s_cbranch_scc0 .Lrstd_miss_973
	v_and_b32_e32 v174, 15, v220
	v_lshrrev_b32_e32 v175, 6, v220
	v_lshlrev_b32_e32 v174, 5, v174
	v_lshl_add_u32 v174, v175, 9, v174
	v_add_u32_e32 v174, 0x20000, v174
	ds_read_b128 v[188:191], v174
	ds_read_b128 v[184:187], v174 offset:16
	s_mul_i32 s6, s65, 0x58
	s_mul_hi_i32 s5, s65, 0x58
	s_waitcnt lgkmcnt(0)
	v_mov_b32_e32 v169, v188
	v_mov_b32_e32 v170, v189
	v_mov_b32_e32 v171, v190
	v_mov_b32_e32 v172, v191
	v_mov_b32_e32 v173, v184
	v_mov_b32_e32 v176, v185
	v_mov_b32_e32 v182, v186
	v_mov_b32_e32 v183, v187
	s_branch .Lrstd_join_973
.Lrstd_miss_973:
	v_lshl_add_u32 v170, s65, 8, v138
	v_ashrrev_i32_e32 v171, 31, v170
	v_lshl_add_u64 v[170:171], v[170:171], 2, s[22:23]
	global_load_dword v169, v[170:171], off
	global_load_dword v172, v[170:171], off offset:64
	global_load_dword v173, v[170:171], off offset:128
	global_load_dword v174, v[170:171], off offset:192
	global_load_dword v175, v[170:171], off offset:512
	global_load_dword v176, v[170:171], off offset:576
	global_load_dword v177, v[170:171], off offset:640
	s_nop 0
	global_load_dword v170, v[170:171], off offset:704
	s_waitcnt vmcnt(0)
	v_fmamk_f32 v169, v169, 0x3a000000, v167
	v_fmamk_f32 v171, v172, 0x3a000000, v167
	v_fmamk_f32 v172, v173, 0x3a000000, v167
	v_fmamk_f32 v173, v174, 0x3a000000, v167
	v_fmamk_f32 v174, v175, 0x3a000000, v167
	v_fmamk_f32 v175, v176, 0x3a000000, v167
	v_mul_f32_e32 v176, 0x4f800000, v169
	v_cmp_gt_f32_e32 vcc, s62, v169
	v_mul_f32_e32 v178, 0x4f800000, v171
	v_cmp_gt_f32_e64 s[2:3], s62, v171
	v_cndmask_b32_e32 v169, v169, v176, vcc
	v_mul_f32_e32 v179, 0x4f800000, v172
	v_cndmask_b32_e64 v171, v171, v178, s[2:3]
	v_cmp_gt_f32_e64 s[4:5], s62, v172
	v_sqrt_f32_e32 v176, v169
	v_mul_f32_e32 v180, 0x4f800000, v173
	v_cndmask_b32_e64 v172, v172, v179, s[4:5]
	v_cmp_gt_f32_e64 s[6:7], s62, v173
	v_sqrt_f32_e32 v178, v171
	v_mul_f32_e32 v181, 0x4f800000, v174
	v_cndmask_b32_e64 v173, v173, v180, s[6:7]
	v_cmp_gt_f32_e64 s[8:9], s62, v174
	v_sqrt_f32_e32 v179, v172
	v_mul_f32_e32 v182, 0x4f800000, v175
	v_cndmask_b32_e64 v174, v174, v181, s[8:9]
	v_cmp_gt_f32_e64 s[10:11], s62, v175
	v_sqrt_f32_e32 v180, v173
	v_sqrt_f32_e32 v181, v174
	v_cndmask_b32_e64 v175, v175, v182, s[10:11]
	v_add_u32_e32 v182, -1, v176
	v_add_u32_e32 v184, -1, v178
	v_fma_f32 v192, -v182, v176, v169
	v_add_u32_e32 v183, 1, v176
	v_add_u32_e32 v186, -1, v179
	v_fma_f32 v194, -v184, v178, v171
	v_cmp_ge_f32_e64 s[12:13], 0, v192
	v_add_u32_e32 v185, 1, v178
	v_add_u32_e32 v188, -1, v180
	v_fma_f32 v193, -v183, v176, v169
	v_fma_f32 v196, -v186, v179, v172
	v_cndmask_b32_e64 v176, v176, v182, s[12:13]
	v_cmp_ge_f32_e64 s[12:13], 0, v194
	v_add_u32_e32 v187, 1, v179
	v_add_u32_e32 v190, -1, v181
	v_fma_f32 v195, -v185, v178, v171
	v_fma_f32 v198, -v188, v180, v173
	v_cndmask_b32_e64 v178, v178, v184, s[12:13]
	v_cmp_ge_f32_e64 s[12:13], 0, v196
	v_add_u32_e32 v189, 1, v180
	v_fma_f32 v197, -v187, v179, v172
	v_fma_f32 v200, -v190, v181, v174
	v_cndmask_b32_e64 v179, v179, v186, s[12:13]
	v_cmp_ge_f32_e64 s[12:13], 0, v198
	v_add_u32_e32 v191, 1, v181
	v_fma_f32 v199, -v189, v180, v173
	v_cndmask_b32_e64 v180, v180, v188, s[12:13]
	v_cmp_ge_f32_e64 s[12:13], 0, v200
	v_fma_f32 v201, -v191, v181, v174
	v_fmamk_f32 v170, v170, 0x3a000000, v167
	v_cndmask_b32_e64 v181, v181, v190, s[12:13]
	v_cmp_lt_f32_e64 s[12:13], 0, v193
	s_nop 1
	v_cndmask_b32_e64 v176, v176, v183, s[12:13]
	v_cmp_lt_f32_e64 s[12:13], 0, v195
	v_mul_f32_e32 v182, 0x37800000, v176
	v_cndmask_b32_e32 v176, v176, v182, vcc
	v_cndmask_b32_e64 v178, v178, v185, s[12:13]
	v_cmp_lt_f32_e64 s[12:13], 0, v197
	v_mul_f32_e32 v183, 0x37800000, v178
	v_cmp_class_f32_e32 vcc, v169, v168
	v_cndmask_b32_e64 v179, v179, v187, s[12:13]
	v_cmp_lt_f32_e64 s[12:13], 0, v199
	v_mul_f32_e32 v184, 0x37800000, v179
	v_cndmask_b32_e64 v178, v178, v183, s[2:3]
	v_cndmask_b32_e64 v180, v180, v189, s[12:13]
	v_cmp_lt_f32_e64 s[12:13], 0, v201
	v_cndmask_b32_e32 v176, v176, v169, vcc
	v_cmp_class_f32_e32 vcc, v171, v168
	v_sqrt_f32_e32 v169, v175
	v_cndmask_b32_e64 v181, v181, v191, s[12:13]
	v_mul_f32_e32 v185, 0x37800000, v180
	v_cndmask_b32_e64 v179, v179, v184, s[4:5]
	v_cndmask_b32_e32 v182, v178, v171, vcc
	v_cmp_class_f32_e32 vcc, v172, v168
	v_mul_f32_e32 v186, 0x37800000, v181
	v_cndmask_b32_e64 v180, v180, v185, s[6:7]
	v_cndmask_b32_e32 v183, v179, v172, vcc
	v_cmp_class_f32_e32 vcc, v173, v168
	v_cndmask_b32_e64 v171, v181, v186, s[8:9]
	v_cmp_class_f32_e64 s[2:3], v175, v168
	v_cndmask_b32_e32 v173, v180, v173, vcc
	v_cmp_class_f32_e32 vcc, v174, v168
	s_mul_i32 s6, s65, 0x58
	s_mul_hi_i32 s5, s65, 0x58
	v_cndmask_b32_e32 v172, v171, v174, vcc
	v_add_u32_e32 v171, -1, v169
	v_fma_f32 v174, -v171, v169, v175
	v_cmp_ge_f32_e32 vcc, 0, v174
	v_add_u32_e32 v174, 1, v169
	s_nop 0
	v_cndmask_b32_e32 v171, v169, v171, vcc
	v_fma_f32 v169, -v174, v169, v175
	v_cmp_lt_f32_e32 vcc, 0, v169
	s_nop 1
	v_cndmask_b32_e32 v169, v171, v174, vcc
	v_fmamk_f32 v174, v177, 0x3a000000, v167
	v_mul_f32_e32 v177, 0x4f800000, v174
	v_cmp_gt_f32_e32 vcc, s62, v174
	v_mul_f32_e32 v171, 0x37800000, v169
	v_cndmask_b32_e64 v169, v169, v171, s[10:11]
	v_cndmask_b32_e32 v174, v174, v177, vcc
	v_sqrt_f32_e32 v177, v174
	v_cndmask_b32_e64 v171, v169, v175, s[2:3]
	v_add_u32_e32 v169, -1, v177
	v_fma_f32 v175, -v169, v177, v174
	v_cmp_ge_f32_e64 s[2:3], 0, v175
	v_add_u32_e32 v175, 1, v177
	s_nop 0
	v_cndmask_b32_e64 v169, v177, v169, s[2:3]
	v_fma_f32 v177, -v175, v177, v174
	v_cmp_lt_f32_e64 s[2:3], 0, v177
	v_mul_f32_e32 v177, 0x4f800000, v170
	s_nop 0
	v_cndmask_b32_e64 v169, v169, v175, s[2:3]
	v_cmp_gt_f32_e64 s[2:3], s62, v170
	v_mul_f32_e32 v175, 0x37800000, v169
	v_cndmask_b32_e32 v169, v169, v175, vcc
	v_cndmask_b32_e64 v177, v170, v177, s[2:3]
	v_sqrt_f32_e32 v178, v177
	v_cmp_class_f32_e32 vcc, v174, v168
	s_nop 1
	v_cndmask_b32_e32 v170, v169, v174, vcc
	v_add_u32_e32 v169, -1, v178
	v_fma_f32 v174, -v169, v178, v177
	v_cmp_ge_f32_e32 vcc, 0, v174
	v_add_u32_e32 v174, 1, v178
	v_fma_f32 v175, -v174, v178, v177
	v_cndmask_b32_e32 v169, v178, v169, vcc
	v_cmp_lt_f32_e32 vcc, 0, v175
	s_nop 1
	v_cndmask_b32_e32 v169, v169, v174, vcc
	v_mul_f32_e32 v174, 0x37800000, v169
	v_cndmask_b32_e64 v169, v169, v174, s[2:3]
	v_cmp_class_f32_e32 vcc, v177, v168
	s_nop 1
	v_cndmask_b32_e32 v169, v169, v177, vcc
	v_and_b32_e32 v192, 15, v220
	v_lshrrev_b32_e32 v193, 6, v220
	v_lshlrev_b32_e32 v192, 5, v192
	v_lshl_add_u32 v192, v193, 9, v192
	v_add_u32_e32 v192, 0x20000, v192
	v_mov_b32_e32 v184, v173
	v_mov_b32_e32 v185, v176
	v_mov_b32_e32 v186, v182
	v_mov_b32_e32 v187, v183
	v_mov_b32_e32 v188, v169
	v_mov_b32_e32 v189, v170
	v_mov_b32_e32 v190, v171
	v_mov_b32_e32 v191, v172
	ds_write_b128 v192, v[188:191]
	ds_write_b128 v192, v[184:187] offset:16
	s_mov_b32 s98, s65
.Lrstd_join_973:
	s_lshl_b32 s2, s66, 1
	s_or_b32 s4, s2, s53
	v_div_scale_f32 v174, s[2:3], v176, v176, 1.0
	v_rcp_f32_e32 v175, v174
	s_ashr_i32 s3, s4, 31
	s_add_u32 s2, s6, s4
	v_fma_f32 v177, -v174, v175, 1.0
	v_fmac_f32_e32 v175, v177, v175
	v_div_scale_f32 v177, vcc, 1.0, v176, 1.0
	v_mul_f32_e32 v178, v177, v175
	v_fma_f32 v179, -v174, v178, v177
	v_fmac_f32_e32 v178, v179, v175
	v_fma_f32 v174, -v174, v178, v177
	v_div_fmas_f32 v174, v174, v175, v178
	v_div_fixup_f32 v174, v174, v176, 1.0
	v_pk_mul_f32 v[124:125], v[124:125], v[174:175] op_sel_hi:[1,0]
	s_addc_u32 s3, s5, s3
	v_mul_f32_e32 v175, 0xbfb8aa3b, v124
	v_exp_f32_e32 v175, v175
	v_mul_f32_e32 v176, 0xbfb8aa3b, v125
	v_exp_f32_e32 v177, v176
	s_lshl_b64 s[2:3], s[2:3], 15
	v_add_f32_e32 v175, 1.0, v175
	v_rcp_f32_e32 v176, v175
	v_add_f32_e32 v175, 1.0, v177
	v_pk_mul_f32 v[120:121], v[120:121], v[174:175] op_sel_hi:[1,0]
	s_add_u32 s2, s47, s2
	v_mul_f32_e32 v177, 0xbfb8aa3b, v120
	v_exp_f32_e32 v178, v177
	v_mul_f32_e32 v177, 0xbfb8aa3b, v121
	v_exp_f32_e32 v179, v177
	v_rcp_f32_e32 v177, v175
	v_add_f32_e32 v175, 1.0, v178
	v_rcp_f32_e32 v178, v175
	v_add_f32_e32 v175, 1.0, v179
	v_pk_mul_f32 v[124:125], v[124:125], v[176:177]
	v_pk_mul_f32 v[116:117], v[116:117], v[174:175] op_sel_hi:[1,0]
	v_rcp_f32_e32 v179, v175
	v_pk_mul_f32 v[116:117], v[116:117], v[124:125]
	v_pk_mul_f32 v[124:125], v[126:127], v[174:175] op_sel_hi:[1,0]
	v_pk_mul_f32 v[112:113], v[112:113], v[174:175] op_sel_hi:[1,0]
	v_mul_f32_e32 v126, 0xbfb8aa3b, v124
	v_mul_f32_e32 v127, 0xbfb8aa3b, v125
	v_exp_f32_e32 v126, v126
	v_exp_f32_e32 v127, v127
	v_pk_mul_f32 v[120:121], v[120:121], v[178:179]
	v_pk_mul_f32 v[122:123], v[122:123], v[174:175] op_sel_hi:[1,0]
	v_pk_mul_f32 v[120:121], v[112:113], v[120:121]
	v_add_f32_e32 v112, 1.0, v126
	v_add_f32_e32 v113, 1.0, v127
	v_mul_f32_e32 v126, 0xbfb8aa3b, v122
	v_mul_f32_e32 v127, 0xbfb8aa3b, v123
	v_exp_f32_e32 v126, v126
	v_exp_f32_e32 v127, v127
	v_rcp_f32_e32 v112, v112
	v_rcp_f32_e32 v113, v113
	v_add_f32_e32 v126, 1.0, v126
	v_add_f32_e32 v127, 1.0, v127
	v_rcp_f32_e32 v126, v126
	v_rcp_f32_e32 v127, v127
	v_pk_mul_f32 v[112:113], v[124:125], v[112:113]
	v_pk_mul_f32 v[118:119], v[118:119], v[174:175] op_sel_hi:[1,0]
	v_pk_mul_f32 v[114:115], v[114:115], v[174:175] op_sel_hi:[1,0]
	v_pk_mul_f32 v[118:119], v[118:119], v[112:113]
	v_pk_mul_f32 v[112:113], v[122:123], v[126:127]
	s_addc_u32 s3, s48, s3
	v_pk_mul_f32 v[122:123], v[114:115], v[112:113]
	v_cvt_pk_bf16_f32 v113, v118, v119
	v_div_scale_f32 v118, s[4:5], v182, v182, 1.0
	v_rcp_f32_e32 v119, v118
	v_cvt_pk_bf16_f32 v114, v120, v121
	v_cvt_pk_bf16_f32 v115, v122, v123
	v_cvt_pk_bf16_f32 v112, v116, v117
	v_fma_f32 v120, -v118, v119, 1.0
	v_fmac_f32_e32 v119, v120, v119
	v_div_scale_f32 v120, vcc, 1.0, v182, 1.0
	v_mul_f32_e32 v121, v120, v119
	v_fma_f32 v122, -v118, v121, v120
	v_fmac_f32_e32 v121, v122, v119
	v_fma_f32 v118, -v118, v121, v120
	v_div_fmas_f32 v118, v118, v119, v121
	v_div_fixup_f32 v118, v118, v182, 1.0
	v_pk_mul_f32 v[108:109], v[108:109], v[118:119] op_sel_hi:[1,0]
	v_lshl_add_u64 v[116:117], s[2:3], 0, v[140:141]
	v_mul_f32_e32 v119, 0xbfb8aa3b, v108
	v_mul_f32_e32 v120, 0xbfb8aa3b, v109
	v_exp_f32_e32 v119, v119
	v_exp_f32_e32 v120, v120
	v_lshl_add_u64 v[116:117], v[116:117], 0, v[136:137]
	global_store_dwordx4 v[116:117], v[112:115], off
	v_pk_mul_f32 v[104:105], v[104:105], v[118:119] op_sel_hi:[1,0]
	v_pk_mul_f32 v[100:101], v[100:101], v[118:119] op_sel_hi:[1,0]
	v_add_f32_e32 v112, 1.0, v119
	v_add_f32_e32 v113, 1.0, v120
	v_rcp_f32_e32 v112, v112
	v_mul_f32_e32 v114, 0xbfb8aa3b, v104
	v_mul_f32_e32 v115, 0xbfb8aa3b, v105
	v_rcp_f32_e32 v113, v113
	v_exp_f32_e32 v114, v114
	v_exp_f32_e32 v115, v115
	v_pk_mul_f32 v[96:97], v[96:97], v[118:119] op_sel_hi:[1,0]
	v_pk_mul_f32 v[108:109], v[108:109], v[112:113]
	v_add_f32_e32 v114, 1.0, v114
	v_add_f32_e32 v115, 1.0, v115
	v_pk_mul_f32 v[100:101], v[100:101], v[108:109]
	v_pk_mul_f32 v[108:109], v[110:111], v[118:119] op_sel_hi:[1,0]
	v_rcp_f32_e32 v114, v114
	v_rcp_f32_e32 v115, v115
	v_mul_f32_e32 v110, 0xbfb8aa3b, v108
	v_mul_f32_e32 v111, 0xbfb8aa3b, v109
	v_exp_f32_e32 v110, v110
	v_exp_f32_e32 v111, v111
	v_pk_mul_f32 v[104:105], v[104:105], v[114:115]
	v_pk_mul_f32 v[106:107], v[106:107], v[118:119] op_sel_hi:[1,0]
	v_pk_mul_f32 v[104:105], v[96:97], v[104:105]
	v_add_f32_e32 v96, 1.0, v110
	v_add_f32_e32 v97, 1.0, v111
	v_mul_f32_e32 v110, 0xbfb8aa3b, v106
	v_mul_f32_e32 v111, 0xbfb8aa3b, v107
	v_exp_f32_e32 v110, v110
	v_exp_f32_e32 v111, v111
	v_rcp_f32_e32 v96, v96
	v_rcp_f32_e32 v97, v97
	v_add_f32_e32 v110, 1.0, v110
	v_add_f32_e32 v111, 1.0, v111
	v_rcp_f32_e32 v110, v110
	v_rcp_f32_e32 v111, v111
	v_pk_mul_f32 v[96:97], v[108:109], v[96:97]
	v_pk_mul_f32 v[102:103], v[102:103], v[118:119] op_sel_hi:[1,0]
	v_pk_mul_f32 v[98:99], v[98:99], v[118:119] op_sel_hi:[1,0]
	v_pk_mul_f32 v[102:103], v[102:103], v[96:97]
	v_pk_mul_f32 v[96:97], v[106:107], v[110:111]
	s_nop 0
	v_pk_mul_f32 v[106:107], v[98:99], v[96:97]
	v_cvt_pk_bf16_f32 v97, v102, v103
	v_div_scale_f32 v102, s[4:5], v183, v183, 1.0
	v_rcp_f32_e32 v103, v102
	v_cvt_pk_bf16_f32 v98, v104, v105
	v_cvt_pk_bf16_f32 v99, v106, v107
	v_cvt_pk_bf16_f32 v96, v100, v101
	v_fma_f32 v104, -v102, v103, 1.0
	v_fmac_f32_e32 v103, v104, v103
	v_div_scale_f32 v104, vcc, 1.0, v183, 1.0
	v_mul_f32_e32 v105, v104, v103
	v_fma_f32 v106, -v102, v105, v104
	v_fmac_f32_e32 v105, v106, v103
	v_fma_f32 v102, -v102, v105, v104
	v_div_fmas_f32 v102, v102, v103, v105
	v_div_fixup_f32 v102, v102, v183, 1.0
	v_pk_mul_f32 v[92:93], v[92:93], v[102:103] op_sel_hi:[1,0]
	v_lshl_add_u64 v[100:101], s[2:3], 0, v[142:143]
	v_mul_f32_e32 v103, 0xbfb8aa3b, v92
	v_mul_f32_e32 v104, 0xbfb8aa3b, v93
	v_exp_f32_e32 v103, v103
	v_exp_f32_e32 v104, v104
	v_lshl_add_u64 v[100:101], v[100:101], 0, v[136:137]
	global_store_dwordx4 v[100:101], v[96:99], off
	v_pk_mul_f32 v[88:89], v[88:89], v[102:103] op_sel_hi:[1,0]
	v_pk_mul_f32 v[84:85], v[84:85], v[102:103] op_sel_hi:[1,0]
	v_add_f32_e32 v96, 1.0, v103
	v_add_f32_e32 v97, 1.0, v104
	v_rcp_f32_e32 v96, v96
	v_mul_f32_e32 v98, 0xbfb8aa3b, v88
	v_mul_f32_e32 v99, 0xbfb8aa3b, v89
	v_rcp_f32_e32 v97, v97
	v_exp_f32_e32 v98, v98
	v_exp_f32_e32 v99, v99
	v_pk_mul_f32 v[80:81], v[80:81], v[102:103] op_sel_hi:[1,0]
	v_pk_mul_f32 v[92:93], v[92:93], v[96:97]
	v_add_f32_e32 v98, 1.0, v98
	v_add_f32_e32 v99, 1.0, v99
	v_pk_mul_f32 v[84:85], v[84:85], v[92:93]
	v_pk_mul_f32 v[92:93], v[94:95], v[102:103] op_sel_hi:[1,0]
	v_rcp_f32_e32 v98, v98
	v_rcp_f32_e32 v99, v99
	v_mul_f32_e32 v94, 0xbfb8aa3b, v92
	v_mul_f32_e32 v95, 0xbfb8aa3b, v93
	v_exp_f32_e32 v94, v94
	v_exp_f32_e32 v95, v95
	v_pk_mul_f32 v[88:89], v[88:89], v[98:99]
	v_pk_mul_f32 v[90:91], v[90:91], v[102:103] op_sel_hi:[1,0]
	v_pk_mul_f32 v[88:89], v[80:81], v[88:89]
	v_add_f32_e32 v80, 1.0, v94
	v_add_f32_e32 v81, 1.0, v95
	v_mul_f32_e32 v94, 0xbfb8aa3b, v90
	v_mul_f32_e32 v95, 0xbfb8aa3b, v91
	v_exp_f32_e32 v94, v94
	v_exp_f32_e32 v95, v95
	v_rcp_f32_e32 v80, v80
	v_rcp_f32_e32 v81, v81
	v_add_f32_e32 v94, 1.0, v94
	v_add_f32_e32 v95, 1.0, v95
	v_rcp_f32_e32 v94, v94
	v_rcp_f32_e32 v95, v95
	v_pk_mul_f32 v[80:81], v[92:93], v[80:81]
	v_pk_mul_f32 v[86:87], v[86:87], v[102:103] op_sel_hi:[1,0]
	v_pk_mul_f32 v[82:83], v[82:83], v[102:103] op_sel_hi:[1,0]
	v_pk_mul_f32 v[86:87], v[86:87], v[80:81]
	v_pk_mul_f32 v[80:81], v[90:91], v[94:95]
	s_nop 0
	v_pk_mul_f32 v[90:91], v[82:83], v[80:81]
	v_cvt_pk_bf16_f32 v81, v86, v87
	v_div_scale_f32 v86, s[4:5], v173, v173, 1.0
	v_rcp_f32_e32 v87, v86
	v_cvt_pk_bf16_f32 v82, v88, v89
	v_cvt_pk_bf16_f32 v83, v90, v91
	v_cvt_pk_bf16_f32 v80, v84, v85
	v_fma_f32 v88, -v86, v87, 1.0
	v_fmac_f32_e32 v87, v88, v87
	v_div_scale_f32 v88, vcc, 1.0, v173, 1.0
	v_mul_f32_e32 v89, v88, v87
	v_fma_f32 v90, -v86, v89, v88
	v_fmac_f32_e32 v89, v90, v87
	v_fma_f32 v86, -v86, v89, v88
	v_div_fmas_f32 v86, v86, v87, v89
	v_div_fixup_f32 v86, v86, v173, 1.0
	v_pk_mul_f32 v[76:77], v[76:77], v[86:87] op_sel_hi:[1,0]
	v_lshl_add_u64 v[84:85], s[2:3], 0, v[144:145]
	v_mul_f32_e32 v87, 0xbfb8aa3b, v76
	v_mul_f32_e32 v88, 0xbfb8aa3b, v77
	v_exp_f32_e32 v87, v87
	v_exp_f32_e32 v88, v88
	v_lshl_add_u64 v[84:85], v[84:85], 0, v[136:137]
	global_store_dwordx4 v[84:85], v[80:83], off
	v_pk_mul_f32 v[72:73], v[72:73], v[86:87] op_sel_hi:[1,0]
	v_pk_mul_f32 v[68:69], v[68:69], v[86:87] op_sel_hi:[1,0]
	v_add_f32_e32 v80, 1.0, v87
	v_add_f32_e32 v81, 1.0, v88
	v_rcp_f32_e32 v80, v80
	v_mul_f32_e32 v82, 0xbfb8aa3b, v72
	v_mul_f32_e32 v83, 0xbfb8aa3b, v73
	v_rcp_f32_e32 v81, v81
	v_exp_f32_e32 v82, v82
	v_exp_f32_e32 v83, v83
	v_pk_mul_f32 v[64:65], v[64:65], v[86:87] op_sel_hi:[1,0]
	v_pk_mul_f32 v[76:77], v[76:77], v[80:81]
	v_add_f32_e32 v82, 1.0, v82
	v_add_f32_e32 v83, 1.0, v83
	v_pk_mul_f32 v[68:69], v[68:69], v[76:77]
	v_pk_mul_f32 v[76:77], v[78:79], v[86:87] op_sel_hi:[1,0]
	v_rcp_f32_e32 v82, v82
	v_rcp_f32_e32 v83, v83
	v_mul_f32_e32 v78, 0xbfb8aa3b, v76
	v_mul_f32_e32 v79, 0xbfb8aa3b, v77
	v_exp_f32_e32 v78, v78
	v_exp_f32_e32 v79, v79
	v_pk_mul_f32 v[72:73], v[72:73], v[82:83]
	v_pk_mul_f32 v[74:75], v[74:75], v[86:87] op_sel_hi:[1,0]
	v_pk_mul_f32 v[72:73], v[64:65], v[72:73]
	v_add_f32_e32 v64, 1.0, v78
	v_add_f32_e32 v65, 1.0, v79
	v_mul_f32_e32 v78, 0xbfb8aa3b, v74
	v_mul_f32_e32 v79, 0xbfb8aa3b, v75
	v_exp_f32_e32 v78, v78
	v_exp_f32_e32 v79, v79
	v_rcp_f32_e32 v64, v64
	v_rcp_f32_e32 v65, v65
	v_add_f32_e32 v78, 1.0, v78
	v_add_f32_e32 v79, 1.0, v79
	v_rcp_f32_e32 v78, v78
	v_rcp_f32_e32 v79, v79
	v_pk_mul_f32 v[64:65], v[76:77], v[64:65]
	v_pk_mul_f32 v[70:71], v[70:71], v[86:87] op_sel_hi:[1,0]
	v_pk_mul_f32 v[66:67], v[66:67], v[86:87] op_sel_hi:[1,0]
	v_pk_mul_f32 v[70:71], v[70:71], v[64:65]
	v_pk_mul_f32 v[64:65], v[74:75], v[78:79]
	s_nop 0
	v_pk_mul_f32 v[74:75], v[66:67], v[64:65]
	v_cvt_pk_bf16_f32 v65, v70, v71
	v_div_scale_f32 v70, s[4:5], v172, v172, 1.0
	v_rcp_f32_e32 v71, v70
	v_cvt_pk_bf16_f32 v66, v72, v73
	v_cvt_pk_bf16_f32 v67, v74, v75
	v_cvt_pk_bf16_f32 v64, v68, v69
	v_fma_f32 v72, -v70, v71, 1.0
	v_fmac_f32_e32 v71, v72, v71
	v_div_scale_f32 v72, vcc, 1.0, v172, 1.0
	v_mul_f32_e32 v73, v72, v71
	v_fma_f32 v74, -v70, v73, v72
	v_fmac_f32_e32 v73, v74, v71
	v_fma_f32 v70, -v70, v73, v72
	v_div_fmas_f32 v70, v70, v71, v73
	v_div_fixup_f32 v70, v70, v172, 1.0
	v_pk_mul_f32 v[60:61], v[60:61], v[70:71] op_sel_hi:[1,0]
	v_lshl_add_u64 v[68:69], s[2:3], 0, v[146:147]
	v_mul_f32_e32 v71, 0xbfb8aa3b, v60
	v_mul_f32_e32 v72, 0xbfb8aa3b, v61
	v_exp_f32_e32 v71, v71
	v_exp_f32_e32 v72, v72
	v_lshl_add_u64 v[68:69], v[68:69], 0, v[136:137]
	global_store_dwordx4 v[68:69], v[64:67], off
	v_pk_mul_f32 v[56:57], v[56:57], v[70:71] op_sel_hi:[1,0]
	v_pk_mul_f32 v[52:53], v[52:53], v[70:71] op_sel_hi:[1,0]
	v_add_f32_e32 v64, 1.0, v71
	v_add_f32_e32 v65, 1.0, v72
	v_rcp_f32_e32 v64, v64
	v_mul_f32_e32 v66, 0xbfb8aa3b, v56
	v_mul_f32_e32 v67, 0xbfb8aa3b, v57
	v_rcp_f32_e32 v65, v65
	v_exp_f32_e32 v66, v66
	v_exp_f32_e32 v67, v67
	v_pk_mul_f32 v[48:49], v[48:49], v[70:71] op_sel_hi:[1,0]
	v_pk_mul_f32 v[60:61], v[60:61], v[64:65]
	v_add_f32_e32 v66, 1.0, v66
	v_add_f32_e32 v67, 1.0, v67
	v_pk_mul_f32 v[52:53], v[52:53], v[60:61]
	v_pk_mul_f32 v[60:61], v[62:63], v[70:71] op_sel_hi:[1,0]
	v_rcp_f32_e32 v66, v66
	v_rcp_f32_e32 v67, v67
	v_mul_f32_e32 v62, 0xbfb8aa3b, v60
	v_mul_f32_e32 v63, 0xbfb8aa3b, v61
	v_exp_f32_e32 v62, v62
	v_exp_f32_e32 v63, v63
	v_pk_mul_f32 v[56:57], v[56:57], v[66:67]
	v_pk_mul_f32 v[58:59], v[58:59], v[70:71] op_sel_hi:[1,0]
	v_pk_mul_f32 v[56:57], v[48:49], v[56:57]
	v_add_f32_e32 v48, 1.0, v62
	v_add_f32_e32 v49, 1.0, v63
	v_mul_f32_e32 v62, 0xbfb8aa3b, v58
	v_mul_f32_e32 v63, 0xbfb8aa3b, v59
	v_exp_f32_e32 v62, v62
	v_exp_f32_e32 v63, v63
	v_rcp_f32_e32 v48, v48
	v_rcp_f32_e32 v49, v49
	v_add_f32_e32 v62, 1.0, v62
	v_add_f32_e32 v63, 1.0, v63
	v_rcp_f32_e32 v62, v62
	v_rcp_f32_e32 v63, v63
	v_pk_mul_f32 v[48:49], v[60:61], v[48:49]
	v_pk_mul_f32 v[54:55], v[54:55], v[70:71] op_sel_hi:[1,0]
	v_pk_mul_f32 v[50:51], v[50:51], v[70:71] op_sel_hi:[1,0]
	v_pk_mul_f32 v[54:55], v[54:55], v[48:49]
	v_pk_mul_f32 v[48:49], v[58:59], v[62:63]
	s_nop 0
	v_pk_mul_f32 v[58:59], v[50:51], v[48:49]
	v_cvt_pk_bf16_f32 v49, v54, v55
	v_div_scale_f32 v54, s[4:5], v171, v171, 1.0
	v_rcp_f32_e32 v55, v54
	v_cvt_pk_bf16_f32 v50, v56, v57
	v_cvt_pk_bf16_f32 v51, v58, v59
	v_cvt_pk_bf16_f32 v48, v52, v53
	v_fma_f32 v56, -v54, v55, 1.0
	v_fmac_f32_e32 v55, v56, v55
	v_div_scale_f32 v56, vcc, 1.0, v171, 1.0
	v_mul_f32_e32 v57, v56, v55
	v_fma_f32 v58, -v54, v57, v56
	v_fmac_f32_e32 v57, v58, v55
	v_fma_f32 v54, -v54, v57, v56
	v_div_fmas_f32 v54, v54, v55, v57
	v_div_fixup_f32 v54, v54, v171, 1.0
	v_pk_mul_f32 v[44:45], v[44:45], v[54:55] op_sel_hi:[1,0]
	v_lshl_add_u64 v[52:53], s[2:3], 0, v[148:149]
	v_mul_f32_e32 v55, 0xbfb8aa3b, v44
	v_mul_f32_e32 v56, 0xbfb8aa3b, v45
	v_exp_f32_e32 v55, v55
	v_exp_f32_e32 v56, v56
	v_lshl_add_u64 v[52:53], v[52:53], 0, v[136:137]
	global_store_dwordx4 v[52:53], v[48:51], off
	v_pk_mul_f32 v[40:41], v[40:41], v[54:55] op_sel_hi:[1,0]
	v_pk_mul_f32 v[36:37], v[36:37], v[54:55] op_sel_hi:[1,0]
	v_add_f32_e32 v48, 1.0, v55
	v_add_f32_e32 v49, 1.0, v56
	v_rcp_f32_e32 v48, v48
	v_mul_f32_e32 v50, 0xbfb8aa3b, v40
	v_mul_f32_e32 v51, 0xbfb8aa3b, v41
	v_rcp_f32_e32 v49, v49
	v_exp_f32_e32 v50, v50
	v_exp_f32_e32 v51, v51
	v_pk_mul_f32 v[32:33], v[32:33], v[54:55] op_sel_hi:[1,0]
	v_pk_mul_f32 v[44:45], v[44:45], v[48:49]
	v_add_f32_e32 v50, 1.0, v50
	v_add_f32_e32 v51, 1.0, v51
	v_pk_mul_f32 v[36:37], v[36:37], v[44:45]
	v_pk_mul_f32 v[44:45], v[46:47], v[54:55] op_sel_hi:[1,0]
	v_rcp_f32_e32 v50, v50
	v_rcp_f32_e32 v51, v51
	v_mul_f32_e32 v46, 0xbfb8aa3b, v44
	v_mul_f32_e32 v47, 0xbfb8aa3b, v45
	v_exp_f32_e32 v46, v46
	v_exp_f32_e32 v47, v47
	v_pk_mul_f32 v[40:41], v[40:41], v[50:51]
	v_pk_mul_f32 v[42:43], v[42:43], v[54:55] op_sel_hi:[1,0]
	v_pk_mul_f32 v[40:41], v[32:33], v[40:41]
	v_add_f32_e32 v32, 1.0, v46
	v_add_f32_e32 v33, 1.0, v47
	v_mul_f32_e32 v46, 0xbfb8aa3b, v42
	v_mul_f32_e32 v47, 0xbfb8aa3b, v43
	v_exp_f32_e32 v46, v46
	v_exp_f32_e32 v47, v47
	v_rcp_f32_e32 v32, v32
	v_rcp_f32_e32 v33, v33
	v_add_f32_e32 v46, 1.0, v46
	v_add_f32_e32 v47, 1.0, v47
	v_rcp_f32_e32 v46, v46
	v_rcp_f32_e32 v47, v47
	v_pk_mul_f32 v[32:33], v[44:45], v[32:33]
	v_pk_mul_f32 v[38:39], v[38:39], v[54:55] op_sel_hi:[1,0]
	v_pk_mul_f32 v[34:35], v[34:35], v[54:55] op_sel_hi:[1,0]
	v_pk_mul_f32 v[38:39], v[38:39], v[32:33]
	v_pk_mul_f32 v[32:33], v[42:43], v[46:47]
	s_nop 0
	v_pk_mul_f32 v[42:43], v[34:35], v[32:33]
	v_cvt_pk_bf16_f32 v33, v38, v39
	v_div_scale_f32 v38, s[4:5], v170, v170, 1.0
	v_rcp_f32_e32 v39, v38
	v_cvt_pk_bf16_f32 v34, v40, v41
	v_cvt_pk_bf16_f32 v35, v42, v43
	v_cvt_pk_bf16_f32 v32, v36, v37
	v_fma_f32 v40, -v38, v39, 1.0
	v_fmac_f32_e32 v39, v40, v39
	v_div_scale_f32 v40, vcc, 1.0, v170, 1.0
	v_mul_f32_e32 v41, v40, v39
	v_fma_f32 v42, -v38, v41, v40
	v_fmac_f32_e32 v41, v42, v39
	v_fma_f32 v38, -v38, v41, v40
	v_div_fmas_f32 v38, v38, v39, v41
	v_div_fixup_f32 v38, v38, v170, 1.0
	v_pk_mul_f32 v[28:29], v[28:29], v[38:39] op_sel_hi:[1,0]
	v_lshl_add_u64 v[36:37], s[2:3], 0, v[150:151]
	v_mul_f32_e32 v39, 0xbfb8aa3b, v28
	v_mul_f32_e32 v40, 0xbfb8aa3b, v29
	v_exp_f32_e32 v39, v39
	v_exp_f32_e32 v40, v40
	v_lshl_add_u64 v[36:37], v[36:37], 0, v[136:137]
	global_store_dwordx4 v[36:37], v[32:35], off
	v_pk_mul_f32 v[24:25], v[24:25], v[38:39] op_sel_hi:[1,0]
	v_pk_mul_f32 v[20:21], v[20:21], v[38:39] op_sel_hi:[1,0]
	v_add_f32_e32 v32, 1.0, v39
	v_add_f32_e32 v33, 1.0, v40
	v_rcp_f32_e32 v32, v32
	v_mul_f32_e32 v34, 0xbfb8aa3b, v24
	v_mul_f32_e32 v35, 0xbfb8aa3b, v25
	v_rcp_f32_e32 v33, v33
	v_exp_f32_e32 v34, v34
	v_exp_f32_e32 v35, v35
	v_pk_mul_f32 v[16:17], v[16:17], v[38:39] op_sel_hi:[1,0]
	v_pk_mul_f32 v[28:29], v[28:29], v[32:33]
	v_add_f32_e32 v34, 1.0, v34
	v_add_f32_e32 v35, 1.0, v35
	v_pk_mul_f32 v[20:21], v[20:21], v[28:29]
	v_pk_mul_f32 v[28:29], v[30:31], v[38:39] op_sel_hi:[1,0]
	v_rcp_f32_e32 v34, v34
	v_rcp_f32_e32 v35, v35
	v_mul_f32_e32 v30, 0xbfb8aa3b, v28
	v_mul_f32_e32 v31, 0xbfb8aa3b, v29
	v_exp_f32_e32 v30, v30
	v_exp_f32_e32 v31, v31
	v_pk_mul_f32 v[24:25], v[24:25], v[34:35]
	v_pk_mul_f32 v[26:27], v[26:27], v[38:39] op_sel_hi:[1,0]
	v_pk_mul_f32 v[24:25], v[16:17], v[24:25]
	v_add_f32_e32 v16, 1.0, v30
	v_add_f32_e32 v17, 1.0, v31
	v_mul_f32_e32 v30, 0xbfb8aa3b, v26
	v_mul_f32_e32 v31, 0xbfb8aa3b, v27
	v_exp_f32_e32 v30, v30
	v_exp_f32_e32 v31, v31
	v_rcp_f32_e32 v16, v16
	v_rcp_f32_e32 v17, v17
	v_add_f32_e32 v30, 1.0, v30
	v_add_f32_e32 v31, 1.0, v31
	v_rcp_f32_e32 v30, v30
	v_rcp_f32_e32 v31, v31
	v_pk_mul_f32 v[16:17], v[28:29], v[16:17]
	v_pk_mul_f32 v[22:23], v[22:23], v[38:39] op_sel_hi:[1,0]
	v_pk_mul_f32 v[18:19], v[18:19], v[38:39] op_sel_hi:[1,0]
	v_pk_mul_f32 v[22:23], v[22:23], v[16:17]
	v_pk_mul_f32 v[16:17], v[26:27], v[30:31]
	s_nop 0
	v_pk_mul_f32 v[26:27], v[18:19], v[16:17]
	v_cvt_pk_bf16_f32 v17, v22, v23
	v_div_scale_f32 v22, s[4:5], v169, v169, 1.0
	v_rcp_f32_e32 v23, v22
	v_cvt_pk_bf16_f32 v18, v24, v25
	v_cvt_pk_bf16_f32 v19, v26, v27
	v_cvt_pk_bf16_f32 v16, v20, v21
	v_fma_f32 v24, -v22, v23, 1.0
	v_fmac_f32_e32 v23, v24, v23
	v_div_scale_f32 v24, vcc, 1.0, v169, 1.0
	v_mul_f32_e32 v25, v24, v23
	v_fma_f32 v26, -v22, v25, v24
	v_fmac_f32_e32 v25, v26, v23
	v_fma_f32 v22, -v22, v25, v24
	v_div_fmas_f32 v22, v22, v23, v25
	v_div_fixup_f32 v22, v22, v169, 1.0
	v_pk_mul_f32 v[12:13], v[12:13], v[22:23] op_sel_hi:[1,0]
	v_lshl_add_u64 v[20:21], s[2:3], 0, v[152:153]
	v_mul_f32_e32 v23, 0xbfb8aa3b, v12
	v_mul_f32_e32 v24, 0xbfb8aa3b, v13
	v_exp_f32_e32 v23, v23
	v_exp_f32_e32 v24, v24
	v_lshl_add_u64 v[20:21], v[20:21], 0, v[136:137]
	global_store_dwordx4 v[20:21], v[16:19], off
	v_pk_mul_f32 v[8:9], v[8:9], v[22:23] op_sel_hi:[1,0]
	v_pk_mul_f32 v[4:5], v[4:5], v[22:23] op_sel_hi:[1,0]
	v_add_f32_e32 v16, 1.0, v23
	v_add_f32_e32 v17, 1.0, v24
	v_rcp_f32_e32 v16, v16
	v_mul_f32_e32 v18, 0xbfb8aa3b, v8
	v_mul_f32_e32 v19, 0xbfb8aa3b, v9
	v_rcp_f32_e32 v17, v17
	v_exp_f32_e32 v18, v18
	v_exp_f32_e32 v19, v19
	v_pk_mul_f32 v[0:1], v[0:1], v[22:23] op_sel_hi:[1,0]
	v_pk_mul_f32 v[12:13], v[12:13], v[16:17]
	v_add_f32_e32 v18, 1.0, v18
	v_add_f32_e32 v19, 1.0, v19
	v_pk_mul_f32 v[4:5], v[4:5], v[12:13]
	v_pk_mul_f32 v[12:13], v[14:15], v[22:23] op_sel_hi:[1,0]
	v_rcp_f32_e32 v18, v18
	v_rcp_f32_e32 v19, v19
	v_mul_f32_e32 v14, 0xbfb8aa3b, v12
	v_mul_f32_e32 v15, 0xbfb8aa3b, v13
	v_exp_f32_e32 v14, v14
	v_exp_f32_e32 v15, v15
	v_pk_mul_f32 v[8:9], v[8:9], v[18:19]
	v_pk_mul_f32 v[10:11], v[10:11], v[22:23] op_sel_hi:[1,0]
	v_pk_mul_f32 v[8:9], v[0:1], v[8:9]
	v_add_f32_e32 v0, 1.0, v14
	v_add_f32_e32 v1, 1.0, v15
	v_mul_f32_e32 v14, 0xbfb8aa3b, v10
	v_mul_f32_e32 v15, 0xbfb8aa3b, v11
	v_exp_f32_e32 v14, v14
	v_exp_f32_e32 v15, v15
	v_rcp_f32_e32 v0, v0
	v_rcp_f32_e32 v1, v1
	v_add_f32_e32 v14, 1.0, v14
	v_add_f32_e32 v15, 1.0, v15
	v_rcp_f32_e32 v14, v14
	v_rcp_f32_e32 v15, v15
	v_pk_mul_f32 v[0:1], v[12:13], v[0:1]
	v_pk_mul_f32 v[6:7], v[6:7], v[22:23] op_sel_hi:[1,0]
	v_pk_mul_f32 v[2:3], v[2:3], v[22:23] op_sel_hi:[1,0]
	v_pk_mul_f32 v[6:7], v[6:7], v[0:1]
	v_pk_mul_f32 v[0:1], v[10:11], v[14:15]
	s_and_b64 vcc, exec, s[0:1]
	v_pk_mul_f32 v[10:11], v[2:3], v[0:1]
	v_cvt_pk_bf16_f32 v0, v4, v5
	v_lshl_add_u64 v[4:5], s[2:3], 0, v[154:155]
	v_cvt_pk_bf16_f32 v1, v6, v7
	v_cvt_pk_bf16_f32 v2, v8, v9
	v_cvt_pk_bf16_f32 v3, v10, v11
	v_lshl_add_u64 v[4:5], v[4:5], 0, v[136:137]
	s_mov_b64 s[0:1], -1
	global_store_dwordx4 v[4:5], v[0:3], off
	s_cbranch_vccnz .LBB0_961
	s_andn2_b64 vcc, exec, s[20:21]
	s_cbranch_vccnz .LBB0_960
	s_barrier
	s_branch .LBB0_960

	.amdhsa_kernel _Z8mega_fwd4Args
		.amdhsa_group_segment_fixed_size 0
		.amdhsa_private_segment_fixed_size 0
		.amdhsa_kernarg_size 464
		.amdhsa_user_sgpr_count 2
		.amdhsa_user_sgpr_dispatch_ptr 0
		.amdhsa_user_sgpr_queue_ptr 0
		.amdhsa_user_sgpr_kernarg_segment_ptr 1
		.amdhsa_user_sgpr_dispatch_id 0
		.amdhsa_user_sgpr_kernarg_preload_length 0
		.amdhsa_user_sgpr_kernarg_preload_offset 0
		.amdhsa_user_sgpr_private_segment_size 0
		.amdhsa_uses_dynamic_stack 0
		.amdhsa_enable_private_segment 0
		.amdhsa_system_sgpr_workgroup_id_x 1
		.amdhsa_system_sgpr_workgroup_id_y 0
		.amdhsa_system_sgpr_workgroup_id_z 0
		.amdhsa_system_sgpr_workgroup_info 0
		.amdhsa_system_vgpr_workitem_id 2
		.amdhsa_next_free_vgpr 253
		.amdhsa_next_free_sgpr 102
		.amdhsa_accum_offset 256
		.amdhsa_reserve_vcc 1
		.amdhsa_float_round_mode_32 0
		.amdhsa_float_round_mode_16_64 0
		.amdhsa_float_denorm_mode_32 3
		.amdhsa_float_denorm_mode_16_64 3
		.amdhsa_dx10_clamp 1
		.amdhsa_ieee_mode 1
		.amdhsa_fp16_overflow 0
		.amdhsa_tg_split 0
		.amdhsa_exception_fp_ieee_invalid_op 0
		.amdhsa_exception_fp_denorm_src 0
		.amdhsa_exception_fp_ieee_div_zero 0
		.amdhsa_exception_fp_ieee_overflow 0
		.amdhsa_exception_fp_ieee_underflow 0
		.amdhsa_exception_fp_ieee_inexact 0
		.amdhsa_exception_int_div_zero 0
	.end_amdhsa_kernel

amdhsa.kernels:
  - .agpr_count:     0
    .args:
      - .offset:         0
        .size:           208
        .value_kind:     by_value
      - .offset:         208
        .size:           4
        .value_kind:     hidden_block_count_x
      - .offset:         212
        .size:           4
        .value_kind:     hidden_block_count_y
      - .offset:         216
        .size:           4
        .value_kind:     hidden_block_count_z
      - .offset:         220
        .size:           2
        .value_kind:     hidden_group_size_x
      - .offset:         222
        .size:           2
        .value_kind:     hidden_group_size_y
      - .offset:         224
        .size:           2
        .value_kind:     hidden_group_size_z
      - .offset:         226
        .size:           2
        .value_kind:     hidden_remainder_x
      - .offset:         228
        .size:           2
        .value_kind:     hidden_remainder_y
      - .offset:         230
        .size:           2
        .value_kind:     hidden_remainder_z
      - .offset:         248
        .size:           8
        .value_kind:     hidden_global_offset_x
      - .offset:         256
        .size:           8
        .value_kind:     hidden_global_offset_y
      - .offset:         264
        .size:           8
        .value_kind:     hidden_global_offset_z
      - .offset:         272
        .size:           2
        .value_kind:     hidden_grid_dims
      - .offset:         296
        .size:           8
        .value_kind:     hidden_multigrid_sync_arg
      - .offset:         328
        .size:           4
        .value_kind:     hidden_dynamic_lds_size
    .group_segment_fixed_size: 0
    .kernarg_segment_align: 8
    .kernarg_segment_size: 464
    .language:       OpenCL C
    .language_version:
      - 2
      - 0
    .max_flat_workgroup_size: 512
    .name:           _Z8mega_fwd4Args
    .private_segment_fixed_size: 0
    .sgpr_count:     108
    .sgpr_spill_count: 164
    .symbol:         _Z8mega_fwd4Args.kd
    .uniform_work_group_size: 1
    .uses_dynamic_stack: false
    .vgpr_count:     253
    .vgpr_spill_count: 0
    .wavefront_size: 64
